# v9 plus q/k epilogue of the QKVG GEMM issuing each row group's rope loads before the previous group's stores with counted vmcnt waits
# speedup vs baseline: 1.0036x; 1.0016x over previous
;     __device__ __forceinline__ void operator()(const f32x4 (&acc)[2][2][4][2], const Unit& u, int wr, int wc, int fr, int fq) const {
;     ...
; #pragma unroll
;             for (int ai = 0; ai < 2; ++ai)
; #pragma unroll
;                 for (int m = 0; m < 4; ++m)
; #pragma unroll
;                     for (int bj = 0; bj < 2; ++bj) { const f32x4 a = acc[ai][bj][m][0], b = acc[ai][bj][m][1];
;                         float s = (a[0] * a[0] + a[1] * a[1]) + (a[2] * a[2] + a[3] * a[3]) + (b[0] * b[0] + b[1] * b[1]) + (b[2] * b[2] + b[3] * b[3]);
;                         s = sum_fq4(s);
;                         if (fq == 0) X[((ai * HALF + wr * 64 + m * 16 + fr) * 2 + bj) * 4 + wc] = s; }
.LBB0_258:
	v_mul_f32_e32 v128, v125, v125
	v_mul_f32_e32 v129, v127, v127
	v_fmac_f32_e32 v128, v124, v124
	v_fmac_f32_e32 v129, v126, v126
	v_add_f32_e32 v128, v128, v129
	v_mul_f32_e32 v129, v121, v121
	v_fmac_f32_e32 v129, v120, v120
	v_add_f32_e32 v128, v128, v129
	v_mul_f32_e32 v129, v123, v123
	v_fmac_f32_e32 v129, v122, v122
	v_add_f32_e32 v128, v129, v128
	v_mov_b32_e32 v129, v128
	s_nop 1
	v_permlane16_swap_b32_e32 v128, v129
	v_add_f32_e32 v128, v128, v129
	v_mov_b32_e32 v129, v128
	s_nop 1
	v_permlane32_swap_b32_e32 v128, v129
	s_and_saveexec_b64 s[56:57], s[6:7]
	v_add_f32_e32 v128, v128, v129
	ds_write_b32 v180, v128
	s_or_b64 exec, exec, s[56:57]
	v_mul_f32_e32 v128, v117, v117
	v_mul_f32_e32 v129, v119, v119
	v_fmac_f32_e32 v128, v116, v116
	v_fmac_f32_e32 v129, v118, v118
	v_add_f32_e32 v128, v128, v129
	v_mul_f32_e32 v129, v113, v113
	v_fmac_f32_e32 v129, v112, v112
	v_add_f32_e32 v128, v128, v129
	v_mul_f32_e32 v129, v115, v115
	v_fmac_f32_e32 v129, v114, v114
	v_add_f32_e32 v128, v129, v128
	v_mov_b32_e32 v129, v128
	s_nop 1
	v_permlane16_swap_b32_e32 v128, v129
	v_add_f32_e32 v128, v128, v129
	v_mov_b32_e32 v129, v128
	s_nop 1
	v_permlane32_swap_b32_e32 v128, v129
	s_and_saveexec_b64 s[56:57], s[6:7]
	v_add_f32_e32 v128, v128, v129
	ds_write_b32 v180, v128 offset:16
	s_or_b64 exec, exec, s[56:57]
	v_mul_f32_e32 v128, v109, v109
	v_mul_f32_e32 v129, v111, v111
	v_fmac_f32_e32 v128, v108, v108
	v_fmac_f32_e32 v129, v110, v110
	v_add_f32_e32 v128, v128, v129
	v_mul_f32_e32 v129, v105, v105
	v_fmac_f32_e32 v129, v104, v104
	v_add_f32_e32 v128, v128, v129
	v_mul_f32_e32 v129, v107, v107
	v_fmac_f32_e32 v129, v106, v106
	v_add_f32_e32 v128, v129, v128
	v_mov_b32_e32 v129, v128
	s_nop 1
	v_permlane16_swap_b32_e32 v128, v129
	v_add_f32_e32 v128, v128, v129
	v_mov_b32_e32 v129, v128
	s_nop 1
	v_permlane32_swap_b32_e32 v128, v129
	s_and_saveexec_b64 s[56:57], s[6:7]
	v_add_f32_e32 v128, v128, v129
	ds_write_b32 v181, v128
	s_or_b64 exec, exec, s[56:57]
	v_mul_f32_e32 v128, v101, v101
	v_mul_f32_e32 v129, v103, v103
	v_fmac_f32_e32 v128, v100, v100
	v_fmac_f32_e32 v129, v102, v102
	v_add_f32_e32 v128, v128, v129
	v_mul_f32_e32 v129, v97, v97
	v_fmac_f32_e32 v129, v96, v96
	v_add_f32_e32 v128, v128, v129
	v_mul_f32_e32 v129, v99, v99
	v_fmac_f32_e32 v129, v98, v98
	v_add_f32_e32 v128, v129, v128
	v_mov_b32_e32 v129, v128
	s_nop 1
	v_permlane16_swap_b32_e32 v128, v129
	v_add_f32_e32 v128, v128, v129
	v_mov_b32_e32 v129, v128
	s_nop 1
	v_permlane32_swap_b32_e32 v128, v129
	s_and_saveexec_b64 s[56:57], s[6:7]
	v_add_f32_e32 v128, v128, v129
	ds_write_b32 v181, v128 offset:16
	s_or_b64 exec, exec, s[56:57]
	v_mul_f32_e32 v128, v93, v93
	v_mul_f32_e32 v129, v95, v95
	v_fmac_f32_e32 v128, v92, v92
	v_fmac_f32_e32 v129, v94, v94
	v_add_f32_e32 v128, v128, v129
	v_mul_f32_e32 v129, v89, v89
	v_fmac_f32_e32 v129, v88, v88
	v_add_f32_e32 v128, v128, v129
	v_mul_f32_e32 v129, v91, v91
	v_fmac_f32_e32 v129, v90, v90
	v_add_f32_e32 v128, v129, v128
	v_mov_b32_e32 v129, v128
	s_nop 1
	v_permlane16_swap_b32_e32 v128, v129
	v_add_f32_e32 v128, v128, v129
	v_mov_b32_e32 v129, v128
	s_nop 1
	v_permlane32_swap_b32_e32 v128, v129
	s_and_saveexec_b64 s[56:57], s[6:7]
	v_add_f32_e32 v128, v128, v129
	ds_write_b32 v182, v128
	s_or_b64 exec, exec, s[56:57]
	v_mul_f32_e32 v128, v85, v85
	v_mul_f32_e32 v129, v87, v87
	v_fmac_f32_e32 v128, v84, v84
	v_fmac_f32_e32 v129, v86, v86
	v_add_f32_e32 v128, v128, v129
	v_mul_f32_e32 v129, v81, v81
	v_fmac_f32_e32 v129, v80, v80
	v_add_f32_e32 v128, v128, v129
	v_mul_f32_e32 v129, v83, v83
	v_fmac_f32_e32 v129, v82, v82
	v_add_f32_e32 v128, v129, v128
	v_mov_b32_e32 v129, v128
	s_nop 1
	v_permlane16_swap_b32_e32 v128, v129
	v_add_f32_e32 v128, v128, v129
	v_mov_b32_e32 v129, v128
	s_nop 1
	v_permlane32_swap_b32_e32 v128, v129
	s_and_saveexec_b64 s[56:57], s[6:7]
	v_add_f32_e32 v128, v128, v129
	ds_write_b32 v182, v128 offset:16
	s_or_b64 exec, exec, s[56:57]
	v_mul_f32_e32 v128, v77, v77
	v_mul_f32_e32 v129, v79, v79
	v_fmac_f32_e32 v128, v76, v76
	v_fmac_f32_e32 v129, v78, v78
	v_add_f32_e32 v128, v128, v129
	v_mul_f32_e32 v129, v73, v73
	v_fmac_f32_e32 v129, v72, v72
	v_add_f32_e32 v128, v128, v129
	v_mul_f32_e32 v129, v75, v75
	v_fmac_f32_e32 v129, v74, v74
	v_add_f32_e32 v128, v129, v128
	v_mov_b32_e32 v129, v128
	s_nop 1
	v_permlane16_swap_b32_e32 v128, v129
	v_add_f32_e32 v128, v128, v129
	v_mov_b32_e32 v129, v128
	s_nop 1
	v_permlane32_swap_b32_e32 v128, v129
	s_and_saveexec_b64 s[56:57], s[6:7]
	v_add_f32_e32 v128, v128, v129
	ds_write_b32 v183, v128
	s_or_b64 exec, exec, s[56:57]
	v_mul_f32_e32 v128, v69, v69
	v_mul_f32_e32 v129, v71, v71
	v_fmac_f32_e32 v128, v68, v68
	v_fmac_f32_e32 v129, v70, v70
	v_add_f32_e32 v128, v128, v129
	v_mul_f32_e32 v129, v65, v65
	v_fmac_f32_e32 v129, v64, v64
	v_add_f32_e32 v128, v128, v129
	v_mul_f32_e32 v129, v67, v67
	v_fmac_f32_e32 v129, v66, v66
	v_add_f32_e32 v128, v129, v128
	v_mov_b32_e32 v129, v128
	s_nop 1
	v_permlane16_swap_b32_e32 v128, v129
	v_add_f32_e32 v128, v128, v129
	v_mov_b32_e32 v129, v128
	s_nop 1
	v_permlane32_swap_b32_e32 v128, v129
	s_and_saveexec_b64 s[56:57], s[6:7]
	v_add_f32_e32 v128, v128, v129
	ds_write_b32 v183, v128 offset:16
	s_or_b64 exec, exec, s[56:57]
	v_mul_f32_e32 v128, v61, v61
	v_mul_f32_e32 v129, v63, v63
	v_fmac_f32_e32 v128, v60, v60
	v_fmac_f32_e32 v129, v62, v62
	v_add_f32_e32 v128, v128, v129
	v_mul_f32_e32 v129, v57, v57
	v_fmac_f32_e32 v129, v56, v56
	v_add_f32_e32 v128, v128, v129
	v_mul_f32_e32 v129, v59, v59
	v_fmac_f32_e32 v129, v58, v58
	v_add_f32_e32 v128, v129, v128
	v_mov_b32_e32 v129, v128
	s_nop 1
;     __device__ __forceinline__ void operator()(const f32x4 (&acc)[2][2][4][2], const Unit& u, int wr, int wc, int fr, int fq) const {
;     ...
;                     for (int bj = 0; bj < 2; ++bj) { const f32x4 a = acc[ai][bj][m][0], b = acc[ai][bj][m][1];
;                         float s = (a[0] * a[0] + a[1] * a[1]) + (a[2] * a[2] + a[3] * a[3]) + (b[0] * b[0] + b[1] * b[1]) + (b[2] * b[2] + b[3] * b[3]);
;                         s = sum_fq4(s);
;                         if (fq == 0) X[((ai * HALF + wr * 64 + m * 16 + fr) * 2 + bj) * 4 + wc] = s; }
;             asm volatile("s_waitcnt lgkmcnt(0)" ::: "memory"); __builtin_amdgcn_s_barrier(); asm volatile("" ::: "memory");
;             const float* gsrc = (u.pn < 4) ? qg : kg;
;             const f32x4 g0 = *(const f32x4*)(gsrc + hc), g1 = *(const f32x4*)(gsrc + hc + 4);
;             unsigned char* base; int ldc, colt;
;             if (u.pn < 4) { base = Q; ldc = DM; colt = u.pn * BM; } else { base = Kb; ldc = KVD; colt = 0; }
	v_permlane16_swap_b32_e32 v128, v129
	v_add_f32_e32 v128, v128, v129
	v_mov_b32_e32 v129, v128
	s_nop 1
	v_permlane32_swap_b32_e32 v128, v129
	s_and_saveexec_b64 s[56:57], s[6:7]
	v_add_f32_e32 v128, v128, v129
	ds_write_b32 v184, v128
	s_or_b64 exec, exec, s[56:57]
	v_mul_f32_e32 v128, v53, v53
	v_mul_f32_e32 v129, v55, v55
	v_fmac_f32_e32 v128, v52, v52
	v_fmac_f32_e32 v129, v54, v54
	v_add_f32_e32 v128, v128, v129
	v_mul_f32_e32 v129, v49, v49
	v_fmac_f32_e32 v129, v48, v48
	v_add_f32_e32 v128, v128, v129
	v_mul_f32_e32 v129, v51, v51
	v_fmac_f32_e32 v129, v50, v50
	v_add_f32_e32 v128, v129, v128
	v_mov_b32_e32 v129, v128
	s_nop 1
	v_permlane16_swap_b32_e32 v128, v129
	v_add_f32_e32 v128, v128, v129
	v_mov_b32_e32 v129, v128
	s_nop 1
	v_permlane32_swap_b32_e32 v128, v129
	s_and_saveexec_b64 s[56:57], s[6:7]
	v_add_f32_e32 v128, v128, v129
	ds_write_b32 v184, v128 offset:16
	s_or_b64 exec, exec, s[56:57]
	v_mul_f32_e32 v128, v45, v45
	v_mul_f32_e32 v129, v47, v47
	v_fmac_f32_e32 v128, v44, v44
	v_fmac_f32_e32 v129, v46, v46
	v_add_f32_e32 v128, v128, v129
	v_mul_f32_e32 v129, v41, v41
	v_fmac_f32_e32 v129, v40, v40
	v_add_f32_e32 v128, v128, v129
	v_mul_f32_e32 v129, v43, v43
	v_fmac_f32_e32 v129, v42, v42
	v_add_f32_e32 v128, v129, v128
	v_mov_b32_e32 v129, v128
	s_nop 1
	v_permlane16_swap_b32_e32 v128, v129
	v_add_f32_e32 v128, v128, v129
	v_mov_b32_e32 v129, v128
	s_nop 1
	v_permlane32_swap_b32_e32 v128, v129
	s_and_saveexec_b64 s[56:57], s[6:7]
	v_add_f32_e32 v128, v128, v129
	ds_write_b32 v185, v128
	s_or_b64 exec, exec, s[56:57]
	v_mul_f32_e32 v128, v37, v37
	v_mul_f32_e32 v129, v39, v39
	v_fmac_f32_e32 v128, v36, v36
	v_fmac_f32_e32 v129, v38, v38
	v_add_f32_e32 v128, v128, v129
	v_mul_f32_e32 v129, v33, v33
	v_fmac_f32_e32 v129, v32, v32
	v_add_f32_e32 v128, v128, v129
	v_mul_f32_e32 v129, v35, v35
	v_fmac_f32_e32 v129, v34, v34
	v_add_f32_e32 v128, v129, v128
	v_mov_b32_e32 v129, v128
	s_nop 1
	v_permlane16_swap_b32_e32 v128, v129
	v_add_f32_e32 v128, v128, v129
	v_mov_b32_e32 v129, v128
	s_nop 1
	v_permlane32_swap_b32_e32 v128, v129
	s_and_saveexec_b64 s[56:57], s[6:7]
	v_add_f32_e32 v128, v128, v129
	ds_write_b32 v185, v128 offset:16
	s_or_b64 exec, exec, s[56:57]
	v_mul_f32_e32 v128, v29, v29
	v_mul_f32_e32 v129, v31, v31
	v_fmac_f32_e32 v128, v28, v28
	v_fmac_f32_e32 v129, v30, v30
	v_add_f32_e32 v128, v128, v129
	v_mul_f32_e32 v129, v25, v25
	v_fmac_f32_e32 v129, v24, v24
	v_add_f32_e32 v128, v128, v129
	v_mul_f32_e32 v129, v27, v27
	v_fmac_f32_e32 v129, v26, v26
	v_add_f32_e32 v128, v129, v128
	v_mov_b32_e32 v129, v128
	s_nop 1
	v_permlane16_swap_b32_e32 v128, v129
	v_add_f32_e32 v128, v128, v129
	v_mov_b32_e32 v129, v128
	s_nop 1
	v_permlane32_swap_b32_e32 v128, v129
	s_and_saveexec_b64 s[56:57], s[6:7]
	v_add_f32_e32 v128, v128, v129
	ds_write_b32 v186, v128
	s_or_b64 exec, exec, s[56:57]
	v_mul_f32_e32 v128, v21, v21
	v_mul_f32_e32 v129, v23, v23
	v_fmac_f32_e32 v128, v20, v20
	v_fmac_f32_e32 v129, v22, v22
	v_add_f32_e32 v128, v128, v129
	v_mul_f32_e32 v129, v17, v17
	v_fmac_f32_e32 v129, v16, v16
	v_add_f32_e32 v128, v128, v129
	v_mul_f32_e32 v129, v19, v19
	v_fmac_f32_e32 v129, v18, v18
	v_add_f32_e32 v128, v129, v128
	v_mov_b32_e32 v129, v128
	s_nop 1
	v_permlane16_swap_b32_e32 v128, v129
	v_add_f32_e32 v128, v128, v129
	v_mov_b32_e32 v129, v128
	s_nop 1
	v_permlane32_swap_b32_e32 v128, v129
	s_and_saveexec_b64 s[56:57], s[6:7]
	v_add_f32_e32 v128, v128, v129
	ds_write_b32 v186, v128 offset:16
	s_or_b64 exec, exec, s[56:57]
	v_mul_f32_e32 v128, v13, v13
	v_mul_f32_e32 v129, v15, v15
	v_fmac_f32_e32 v128, v12, v12
	v_fmac_f32_e32 v129, v14, v14
	v_add_f32_e32 v128, v128, v129
	v_mul_f32_e32 v129, v9, v9
	v_fmac_f32_e32 v129, v8, v8
	v_add_f32_e32 v128, v128, v129
	v_mul_f32_e32 v129, v11, v11
	v_fmac_f32_e32 v129, v10, v10
	v_add_f32_e32 v128, v129, v128
	v_mov_b32_e32 v129, v128
	s_nop 1
	v_permlane16_swap_b32_e32 v128, v129
	v_add_f32_e32 v128, v128, v129
	v_mov_b32_e32 v129, v128
	s_nop 1
	v_permlane32_swap_b32_e32 v128, v129
	s_and_saveexec_b64 s[56:57], s[6:7]
	v_add_f32_e32 v128, v128, v129
	ds_write_b32 v187, v128
	s_or_b64 exec, exec, s[56:57]
	v_mul_f32_e32 v128, v5, v5
	v_mul_f32_e32 v129, v7, v7
	v_fmac_f32_e32 v128, v4, v4
	v_fmac_f32_e32 v129, v6, v6
	v_add_f32_e32 v128, v128, v129
	v_mul_f32_e32 v129, v1, v1
	v_fmac_f32_e32 v129, v0, v0
	v_add_f32_e32 v128, v128, v129
	v_mul_f32_e32 v129, v3, v3
	v_fmac_f32_e32 v129, v2, v2
	v_add_f32_e32 v128, v129, v128
	v_mov_b32_e32 v129, v128
	s_nop 1
	v_permlane16_swap_b32_e32 v128, v129
	v_add_f32_e32 v128, v128, v129
	v_mov_b32_e32 v129, v128
	s_nop 1
	v_permlane32_swap_b32_e32 v128, v129
	s_and_saveexec_b64 s[56:57], s[6:7]
	v_add_f32_e32 v128, v128, v129
	ds_write_b32 v187, v128 offset:16
	s_or_b64 exec, exec, s[56:57]
	s_lshl_b32 s16, s54, 8
	s_cmp_eq_u32 s54, 4
	s_cselect_b64 s[56:57], -1, 0
	v_cndmask_b32_e64 v191, v190, 1.0, s[56:57]
	s_and_b64 s[56:57], s[56:57], exec
	s_cselect_b32 s47, 0, s16
	s_cselect_b32 s57, s11, s9
	s_cselect_b32 s56, s10, s8
	s_cselect_b32 s45, s82, 0xc000000
	s_cselect_b32 s16, 8, 10
	s_ashr_i32 s53, s47, 31
	s_waitcnt lgkmcnt(0)
	s_barrier
; #define LAS __attribute__((address_space(3)))
;     __device__ __forceinline__ void operator()(const f32x4 (&acc)[2][2][4][2], const Unit& u, int wr, int wc, int fr, int fq) const {
;     ...
; #pragma unroll
;             for (int ai = 0; ai < 2; ++ai)
; #pragma unroll
;                 for (int m = 0; m < 4; ++m) { const int lr = ai * HALF + wr * 64 + m * 16 + fr, row = u.pm * BM + lr, spos = row & (SEQ - 1);
;                     const f32x4* rp = (const f32x4*)(rope + (size_t)spos * 128 + hc); const f32x4 r0 = rp[0], r1 = rp[1];
; #pragma unroll
;                     for (int bj = 0; bj < 2; ++bj) { const f32x4 sv = *(const LAS f32x4*)(X + (lr * 2 + bj) * 4);
;                         const float rs = __builtin_amdgcn_rsqf(((sv[0] + sv[1]) + (sv[2] + sv[3])) * (1.0f / 128.0f) + RMS_EPS) * (u.pn < 4 ? QSCALE : 1.0f);
;                         const f32x4 a = acc[ai][bj][m][0] * rs * g0, b = acc[ai][bj][m][1] * rs * g1;
;                         u32x2 w; int t0, t1;
;                         t0 = __builtin_amdgcn_cvt_pk_fp8_f32(a[0] * r0[0] - a[1] * r0[1], a[0] * r0[1] + a[1] * r0[0], 0, false);
;                         t0 = __builtin_amdgcn_cvt_pk_fp8_f32(a[2] * r0[2] - a[3] * r0[3], a[2] * r0[3] + a[3] * r0[2], t0, true);
;                         t1 = __builtin_amdgcn_cvt_pk_fp8_f32(b[0] * r1[0] - b[1] * r1[1], b[0] * r1[1] + b[1] * r1[0], 0, false);
;                         t1 = __builtin_amdgcn_cvt_pk_fp8_f32(b[2] * r1[2] - b[3] * r1[3], b[2] * r1[3] + b[3] * r1[2], t1, true);
;                         w.x = (unsigned)t0; w.y = (unsigned)t1;
;                         *(u32x2*)(base + (size_t)row * ldc + colt + bj * HALF + hc) = w; } }
	v_lshlrev_b32_e32 v132, 2, v146
	s_add_u32 s54, s14, s45
	global_load_dwordx4 v[128:131], v132, s[56:57] offset:16
	s_nop 0
	global_load_dwordx4 v[132:135], v132, s[56:57]
	s_addc_u32 s56, s15, 0
	s_lshl_b32 s45, s52, 8
	v_add_u32_e32 v208, s45, v170
	v_lshlrev_b32_e32 v144, 9, v208
	v_and_b32_e32 v144, 0x3f9e00, v144
	v_lshl_add_u64 v[168:169], v[156:157], 0, v[144:145]
	global_load_dwordx4 v[192:195], v[168:169], off
	global_load_dwordx4 v[196:199], v[168:169], off offset:16
	s_add_u32 s52, s54, s47
	v_lshlrev_b32_e32 v144, 5, v170
	s_addc_u32 s53, s56, s53
	s_add_i32 s47, 0, 0x20000
	v_add_u32_e32 v144, s47, v144
	ds_read_b128 v[200:203], v144
	ds_read_b128 v[204:207], v144 offset:16
	v_mov_b32_e32 v212, v145
	v_mov_b32_e32 v210, v145
	v_mov_b32_e32 v211, v145
	s_waitcnt lgkmcnt(0)
	v_mov_b32_e32 v168, v201
	v_mov_b32_e32 v169, v202
	v_mov_b32_e32 v201, v203
	v_mov_b32_e32 v202, v205
	v_mov_b32_e32 v203, v206
	v_mov_b32_e32 v205, v207
	v_pk_add_f32 v[168:169], v[168:169], v[200:201]
	v_pk_add_f32 v[200:201], v[202:203], v[204:205]
	v_add_f32_e32 v144, v168, v169
	v_add_f32_e32 v168, v200, v201
	v_fmamk_f32 v144, v144, 0x3c000000, v189
	v_fmamk_f32 v168, v168, 0x3c000000, v189
	v_rsq_f32_e32 v144, v144
	v_rsq_f32_e32 v200, v168
	v_mov_b32_e32 v213, v145
	v_ashrrev_i32_e32 v209, 31, v208
	v_mul_f32_e32 v144, v191, v144
	v_mul_f32_e32 v200, v191, v200
	v_pk_mul_f32 v[122:123], v[122:123], v[144:145] op_sel_hi:[1,0]
	v_pk_mul_f32 v[116:117], v[116:117], v[200:201] op_sel_hi:[1,0]
	v_pk_mul_f32 v[124:125], v[124:125], v[144:145] op_sel_hi:[1,0]
	v_pk_mul_f32 v[118:119], v[118:119], v[200:201] op_sel_hi:[1,0]
	v_pk_mul_f32 v[126:127], v[126:127], v[144:145] op_sel_hi:[1,0]
	v_pk_mul_f32 v[120:121], v[120:121], v[144:145] op_sel_hi:[1,0]
	v_pk_mul_f32 v[112:113], v[112:113], v[200:201] op_sel_hi:[1,0]
	v_pk_mul_f32 v[114:115], v[114:115], v[200:201] op_sel_hi:[1,0]
	v_lshl_add_u64 v[168:169], s[52:53], 0, v[146:147]
	s_waitcnt vmcnt(0)
	v_pk_mul_f32 v[122:123], v[130:131], v[122:123]
	v_pk_mul_f32 v[116:117], v[132:133], v[116:117]
	v_pk_mul_f32 v[124:125], v[132:133], v[124:125]
	v_pk_mul_f32 v[118:119], v[134:135], v[118:119]
	v_pk_mul_f32 v[126:127], v[134:135], v[126:127]
	v_pk_mul_f32 v[120:121], v[128:129], v[120:121]
	v_pk_mul_f32 v[112:113], v[128:129], v[112:113]
	v_pk_mul_f32 v[214:215], v[192:193], v[116:117]
	v_pk_mul_f32 v[206:207], v[198:199], v[122:123]
	v_pk_mul_f32 v[122:123], v[198:199], v[122:123] op_sel:[1,0] op_sel_hi:[0,1]
	v_pk_mul_f32 v[116:117], v[192:193], v[116:117] op_sel:[1,0] op_sel_hi:[0,1]
	v_add_f32_e32 v122, v122, v123
	v_sub_f32_e32 v123, v214, v215
	v_add_f32_e32 v116, v116, v117
	v_cvt_pk_fp8_f32 v212, v123, v116
	v_pk_mul_f32 v[200:201], v[192:193], v[124:125]
	v_pk_mul_f32 v[124:125], v[192:193], v[124:125] op_sel:[1,0] op_sel_hi:[0,1]
	v_pk_mul_f32 v[192:193], v[194:195], v[118:119]
	v_pk_mul_f32 v[118:119], v[194:195], v[118:119] op_sel:[1,0] op_sel_hi:[0,1]
	v_pk_mul_f32 v[202:203], v[194:195], v[126:127]
	v_pk_mul_f32 v[126:127], v[194:195], v[126:127] op_sel:[1,0] op_sel_hi:[0,1]
	v_pk_mul_f32 v[204:205], v[196:197], v[120:121]
	v_pk_mul_f32 v[120:121], v[196:197], v[120:121] op_sel:[1,0] op_sel_hi:[0,1]
	v_sub_f32_e32 v117, v192, v193
	v_add_f32_e32 v116, v118, v119
	v_sub_f32_e32 v144, v200, v201
	v_add_f32_e32 v124, v124, v125
	v_add_f32_e32 v126, v126, v127
	v_sub_f32_e32 v127, v204, v205
	v_add_f32_e32 v120, v120, v121
	v_cvt_pk_fp8_f32 v212, v117, v116 op_sel:[0,0,1]
	v_pk_mul_f32 v[116:117], v[196:197], v[112:113]
	v_pk_mul_f32 v[112:113], v[196:197], v[112:113] op_sel:[1,0] op_sel_hi:[0,1]
	v_cvt_pk_fp8_f32 v210, v144, v124
	v_cvt_pk_fp8_f32 v211, v127, v120
	v_sub_f32_e32 v116, v116, v117
	v_add_f32_e32 v112, v112, v113
	v_pk_mul_f32 v[114:115], v[130:131], v[114:115]
	v_cvt_pk_fp8_f32 v213, v116, v112
	v_pk_mul_f32 v[112:113], v[198:199], v[114:115]
	v_sub_f32_e32 v125, v202, v203
	v_sub_f32_e32 v121, v206, v207
	v_sub_f32_e32 v116, v112, v113
	v_pk_mul_f32 v[112:113], v[198:199], v[114:115] op_sel:[1,0] op_sel_hi:[0,1]
	v_cvt_pk_fp8_f32 v210, v125, v126 op_sel:[0,0,1]
	v_cvt_pk_fp8_f32 v211, v121, v122 op_sel:[0,0,1]
	v_add_f32_e32 v112, v112, v113
	v_cvt_pk_fp8_f32 v213, v116, v112 op_sel:[0,0,1]
	v_lshlrev_b64 v[216:217], s16, v[208:209]
	v_lshl_add_u64 v[216:217], v[168:169], 0, v[216:217]
	v_add_u32_e32 v192, s45, v172
	v_lshlrev_b32_e32 v112, 9, v192
	v_and_b32_e32 v144, 0x3fbe00, v112
	v_lshl_add_u64 v[116:117], v[156:157], 0, v[144:145]
	global_load_dwordx4 v[112:115], v[116:117], off
	s_nop 0
	global_load_dwordx4 v[116:119], v[116:117], off offset:16
	global_store_dwordx2 v[216:217], v[210:211], off
	global_store_dwordx2 v[216:217], v[212:213], off offset:128
	v_lshlrev_b32_e32 v120, 5, v172
	v_add_u32_e32 v124, s47, v120
	ds_read_b128 v[120:123], v124
	ds_read_b128 v[124:127], v124 offset:16
	v_mov_b32_e32 v194, v145
	v_mov_b32_e32 v195, v145
	v_ashrrev_i32_e32 v193, 31, v192
	s_waitcnt lgkmcnt(1)
	v_mov_b32_e32 v196, v121
	v_mov_b32_e32 v197, v122
	v_mov_b32_e32 v121, v123
	s_waitcnt lgkmcnt(0)
; #define LAS __attribute__((address_space(3)))
;     __device__ __forceinline__ void operator()(const f32x4 (&acc)[2][2][4][2], const Unit& u, int wr, int wc, int fr, int fq) const {
;     ...
;                 for (int m = 0; m < 4; ++m) { const int lr = ai * HALF + wr * 64 + m * 16 + fr, row = u.pm * BM + lr, spos = row & (SEQ - 1);
;                     const f32x4* rp = (const f32x4*)(rope + (size_t)spos * 128 + hc); const f32x4 r0 = rp[0], r1 = rp[1];
; #pragma unroll
;                     for (int bj = 0; bj < 2; ++bj) { const f32x4 sv = *(const LAS f32x4*)(X + (lr * 2 + bj) * 4);
;                         const float rs = __builtin_amdgcn_rsqf(((sv[0] + sv[1]) + (sv[2] + sv[3])) * (1.0f / 128.0f) + RMS_EPS) * (u.pn < 4 ? QSCALE : 1.0f);
;                         const f32x4 a = acc[ai][bj][m][0] * rs * g0, b = acc[ai][bj][m][1] * rs * g1;
;                         u32x2 w; int t0, t1;
;                         t0 = __builtin_amdgcn_cvt_pk_fp8_f32(a[0] * r0[0] - a[1] * r0[1], a[0] * r0[1] + a[1] * r0[0], 0, false);
;                         t0 = __builtin_amdgcn_cvt_pk_fp8_f32(a[2] * r0[2] - a[3] * r0[3], a[2] * r0[3] + a[3] * r0[2], t0, true);
;                         t1 = __builtin_amdgcn_cvt_pk_fp8_f32(b[0] * r1[0] - b[1] * r1[1], b[0] * r1[1] + b[1] * r1[0], 0, false);
;                         t1 = __builtin_amdgcn_cvt_pk_fp8_f32(b[2] * r1[2] - b[3] * r1[3], b[2] * r1[3] + b[3] * r1[2], t1, true);
;                         w.x = (unsigned)t0; w.y = (unsigned)t1;
;                         *(u32x2*)(base + (size_t)row * ldc + colt + bj * HALF + hc) = w; } }
	v_mov_b32_e32 v122, v125
	v_mov_b32_e32 v123, v126
	v_mov_b32_e32 v125, v127
	v_pk_add_f32 v[120:121], v[196:197], v[120:121]
	v_pk_add_f32 v[122:123], v[122:123], v[124:125]
	v_add_f32_e32 v120, v120, v121
	v_add_f32_e32 v121, v122, v123
	v_fmamk_f32 v120, v120, 0x3c000000, v189
	v_fmamk_f32 v121, v121, 0x3c000000, v189
	v_rsq_f32_e32 v122, v120
	v_rsq_f32_e32 v121, v121
	v_mov_b32_e32 v120, v145
	v_mul_f32_e32 v122, v191, v122
	v_mul_f32_e32 v124, v191, v121
	v_pk_mul_f32 v[106:107], v[106:107], v[122:123] op_sel_hi:[1,0]
	v_pk_mul_f32 v[100:101], v[100:101], v[124:125] op_sel_hi:[1,0]
	v_pk_mul_f32 v[106:107], v[130:131], v[106:107]
	v_pk_mul_f32 v[100:101], v[132:133], v[100:101]
	v_pk_mul_f32 v[108:109], v[108:109], v[122:123] op_sel_hi:[1,0]
	v_pk_mul_f32 v[110:111], v[110:111], v[122:123] op_sel_hi:[1,0]
	v_pk_mul_f32 v[104:105], v[104:105], v[122:123] op_sel_hi:[1,0]
	v_pk_mul_f32 v[102:103], v[102:103], v[124:125] op_sel_hi:[1,0]
	v_pk_mul_f32 v[96:97], v[96:97], v[124:125] op_sel_hi:[1,0]
	v_pk_mul_f32 v[110:111], v[134:135], v[110:111]
	v_pk_mul_f32 v[108:109], v[132:133], v[108:109]
	v_pk_mul_f32 v[104:105], v[128:129], v[104:105]
	v_pk_mul_f32 v[102:103], v[134:135], v[102:103]
	v_pk_mul_f32 v[98:99], v[98:99], v[124:125] op_sel_hi:[1,0]
	v_pk_mul_f32 v[96:97], v[128:129], v[96:97]
	v_pk_mul_f32 v[98:99], v[130:131], v[98:99]
	s_waitcnt vmcnt(3)
	v_pk_mul_f32 v[198:199], v[112:113], v[100:101]
	s_waitcnt vmcnt(2)
	v_pk_mul_f32 v[196:197], v[118:119], v[106:107]
	v_pk_mul_f32 v[106:107], v[118:119], v[106:107] op_sel:[1,0] op_sel_hi:[0,1]
	v_pk_mul_f32 v[100:101], v[112:113], v[100:101] op_sel:[1,0] op_sel_hi:[0,1]
	v_add_f32_e32 v106, v106, v107
	v_sub_f32_e32 v107, v198, v199
	v_add_f32_e32 v100, v100, v101
	v_cvt_pk_fp8_f32 v120, v107, v100
	v_pk_mul_f32 v[122:123], v[112:113], v[108:109]
	v_pk_mul_f32 v[108:109], v[112:113], v[108:109] op_sel:[1,0] op_sel_hi:[0,1]
	v_pk_mul_f32 v[124:125], v[114:115], v[110:111]
	v_pk_mul_f32 v[110:111], v[114:115], v[110:111] op_sel:[1,0] op_sel_hi:[0,1]
	v_pk_mul_f32 v[126:127], v[116:117], v[104:105]
	v_pk_mul_f32 v[104:105], v[116:117], v[104:105] op_sel:[1,0] op_sel_hi:[0,1]
	v_pk_mul_f32 v[112:113], v[114:115], v[102:103]
	v_pk_mul_f32 v[102:103], v[114:115], v[102:103] op_sel:[1,0] op_sel_hi:[0,1]
	v_pk_mul_f32 v[114:115], v[116:117], v[96:97]
	v_sub_f32_e32 v121, v122, v123
	v_add_f32_e32 v108, v108, v109
	v_add_f32_e32 v110, v110, v111
	v_sub_f32_e32 v111, v126, v127
	v_add_f32_e32 v104, v104, v105
	v_sub_f32_e32 v101, v112, v113
	v_add_f32_e32 v100, v102, v103
	v_pk_mul_f32 v[96:97], v[116:117], v[96:97] op_sel:[1,0] op_sel_hi:[0,1]
	v_cvt_pk_fp8_f32 v194, v121, v108
	v_cvt_pk_fp8_f32 v195, v111, v104
	v_cvt_pk_fp8_f32 v120, v101, v100 op_sel:[0,0,1]
	v_sub_f32_e32 v100, v114, v115
	v_add_f32_e32 v96, v96, v97
	v_mov_b32_e32 v121, v145
	v_cvt_pk_fp8_f32 v121, v100, v96
	v_pk_mul_f32 v[96:97], v[118:119], v[98:99]
	v_sub_f32_e32 v109, v124, v125
	v_sub_f32_e32 v105, v196, v197
	v_sub_f32_e32 v100, v96, v97
	v_pk_mul_f32 v[96:97], v[118:119], v[98:99] op_sel:[1,0] op_sel_hi:[0,1]
	v_cvt_pk_fp8_f32 v194, v109, v110 op_sel:[0,0,1]
	v_cvt_pk_fp8_f32 v195, v105, v106 op_sel:[0,0,1]
	v_add_f32_e32 v96, v96, v97
	v_cvt_pk_fp8_f32 v121, v100, v96 op_sel:[0,0,1]
	v_lshlrev_b64 v[216:217], s16, v[192:193]
	v_lshl_add_u64 v[216:217], v[168:169], 0, v[216:217]
	v_add_u32_e32 v112, s45, v173
	v_lshlrev_b32_e32 v96, 9, v112
	v_and_b32_e32 v144, 0x3fde00, v96
	v_lshl_add_u64 v[100:101], v[156:157], 0, v[144:145]
	global_load_dwordx4 v[96:99], v[100:101], off
	s_nop 0
	global_load_dwordx4 v[100:103], v[100:101], off offset:16
	global_store_dwordx2 v[216:217], v[194:195], off
	global_store_dwordx2 v[216:217], v[120:121], off offset:128
	v_lshlrev_b32_e32 v104, 5, v173
	v_add_u32_e32 v108, s47, v104
	ds_read_b128 v[104:107], v108
	ds_read_b128 v[108:111], v108 offset:16
	v_mov_b32_e32 v114, v145
	v_mov_b32_e32 v115, v145
	v_ashrrev_i32_e32 v113, 31, v112
	s_waitcnt lgkmcnt(1)
	v_mov_b32_e32 v116, v105
	v_mov_b32_e32 v117, v106
	v_mov_b32_e32 v105, v107
	s_waitcnt lgkmcnt(0)
	v_mov_b32_e32 v106, v109
	v_mov_b32_e32 v107, v110
	v_mov_b32_e32 v109, v111
	v_pk_add_f32 v[104:105], v[116:117], v[104:105]
	v_pk_add_f32 v[106:107], v[106:107], v[108:109]
	v_add_f32_e32 v104, v104, v105
	v_add_f32_e32 v105, v106, v107
	v_fmamk_f32 v104, v104, 0x3c000000, v189
	v_fmamk_f32 v105, v105, 0x3c000000, v189
	v_rsq_f32_e32 v106, v104
	v_rsq_f32_e32 v105, v105
	v_mov_b32_e32 v104, v145
	v_mul_f32_e32 v106, v191, v106
	v_mul_f32_e32 v108, v191, v105
	v_pk_mul_f32 v[92:93], v[92:93], v[106:107] op_sel_hi:[1,0]
	v_pk_mul_f32 v[94:95], v[94:95], v[106:107] op_sel_hi:[1,0]
	v_pk_mul_f32 v[88:89], v[88:89], v[106:107] op_sel_hi:[1,0]
	v_pk_mul_f32 v[90:91], v[90:91], v[106:107] op_sel_hi:[1,0]
	v_pk_mul_f32 v[84:85], v[84:85], v[108:109] op_sel_hi:[1,0]
	v_pk_mul_f32 v[86:87], v[86:87], v[108:109] op_sel_hi:[1,0]
	v_pk_mul_f32 v[80:81], v[80:81], v[108:109] op_sel_hi:[1,0]
	v_pk_mul_f32 v[94:95], v[134:135], v[94:95]
	v_pk_mul_f32 v[92:93], v[132:133], v[92:93]
	v_pk_mul_f32 v[90:91], v[130:131], v[90:91]
	v_pk_mul_f32 v[88:89], v[128:129], v[88:89]
	v_pk_mul_f32 v[84:85], v[132:133], v[84:85]
	v_pk_mul_f32 v[82:83], v[82:83], v[108:109] op_sel_hi:[1,0]
	v_pk_mul_f32 v[86:87], v[134:135], v[86:87]
	v_pk_mul_f32 v[80:81], v[128:129], v[80:81]
	v_pk_mul_f32 v[82:83], v[130:131], v[82:83]
	s_waitcnt vmcnt(3)
	v_pk_mul_f32 v[106:107], v[96:97], v[92:93]
	v_pk_mul_f32 v[92:93], v[96:97], v[92:93] op_sel:[1,0] op_sel_hi:[0,1]
	v_pk_mul_f32 v[108:109], v[98:99], v[94:95]
	v_pk_mul_f32 v[94:95], v[98:99], v[94:95] op_sel:[1,0] op_sel_hi:[0,1]
	s_waitcnt vmcnt(2)
; #define LAS __attribute__((address_space(3)))
;     __device__ __forceinline__ void operator()(const f32x4 (&acc)[2][2][4][2], const Unit& u, int wr, int wc, int fr, int fq) const {
;     ...
;                 for (int m = 0; m < 4; ++m) { const int lr = ai * HALF + wr * 64 + m * 16 + fr, row = u.pm * BM + lr, spos = row & (SEQ - 1);
;                     const f32x4* rp = (const f32x4*)(rope + (size_t)spos * 128 + hc); const f32x4 r0 = rp[0], r1 = rp[1];
; #pragma unroll
;                     for (int bj = 0; bj < 2; ++bj) { const f32x4 sv = *(const LAS f32x4*)(X + (lr * 2 + bj) * 4);
;                         const float rs = __builtin_amdgcn_rsqf(((sv[0] + sv[1]) + (sv[2] + sv[3])) * (1.0f / 128.0f) + RMS_EPS) * (u.pn < 4 ? QSCALE : 1.0f);
;                         const f32x4 a = acc[ai][bj][m][0] * rs * g0, b = acc[ai][bj][m][1] * rs * g1;
;                         u32x2 w; int t0, t1;
;                         t0 = __builtin_amdgcn_cvt_pk_fp8_f32(a[0] * r0[0] - a[1] * r0[1], a[0] * r0[1] + a[1] * r0[0], 0, false);
;                         t0 = __builtin_amdgcn_cvt_pk_fp8_f32(a[2] * r0[2] - a[3] * r0[3], a[2] * r0[3] + a[3] * r0[2], t0, true);
;                         t1 = __builtin_amdgcn_cvt_pk_fp8_f32(b[0] * r1[0] - b[1] * r1[1], b[0] * r1[1] + b[1] * r1[0], 0, false);
;                         t1 = __builtin_amdgcn_cvt_pk_fp8_f32(b[2] * r1[2] - b[3] * r1[3], b[2] * r1[3] + b[3] * r1[2], t1, true);
;                         w.x = (unsigned)t0; w.y = (unsigned)t1;
;                         *(u32x2*)(base + (size_t)row * ldc + colt + bj * HALF + hc) = w; } }
	v_pk_mul_f32 v[110:111], v[100:101], v[88:89]
	v_pk_mul_f32 v[88:89], v[100:101], v[88:89] op_sel:[1,0] op_sel_hi:[0,1]
	v_pk_mul_f32 v[116:117], v[102:103], v[90:91]
	v_pk_mul_f32 v[90:91], v[102:103], v[90:91] op_sel:[1,0] op_sel_hi:[0,1]
	v_pk_mul_f32 v[118:119], v[96:97], v[84:85]
	v_pk_mul_f32 v[84:85], v[96:97], v[84:85] op_sel:[1,0] op_sel_hi:[0,1]
	v_pk_mul_f32 v[96:97], v[98:99], v[86:87]
	v_pk_mul_f32 v[86:87], v[98:99], v[86:87] op_sel:[1,0] op_sel_hi:[0,1]
	v_pk_mul_f32 v[98:99], v[100:101], v[80:81]
	v_sub_f32_e32 v105, v106, v107
	v_add_f32_e32 v92, v92, v93
	v_add_f32_e32 v94, v94, v95
	v_sub_f32_e32 v95, v110, v111
	v_add_f32_e32 v88, v88, v89
	v_add_f32_e32 v90, v90, v91
	v_sub_f32_e32 v91, v118, v119
	v_add_f32_e32 v84, v84, v85
	v_pk_mul_f32 v[80:81], v[100:101], v[80:81] op_sel:[1,0] op_sel_hi:[0,1]
	v_cvt_pk_fp8_f32 v114, v105, v92
	v_cvt_pk_fp8_f32 v115, v95, v88
	v_cvt_pk_fp8_f32 v104, v91, v84
	v_sub_f32_e32 v84, v98, v99
	v_add_f32_e32 v80, v80, v81
	v_mov_b32_e32 v105, v145
	v_cvt_pk_fp8_f32 v105, v84, v80
	v_pk_mul_f32 v[80:81], v[102:103], v[82:83]
	v_sub_f32_e32 v93, v108, v109
	v_sub_f32_e32 v89, v116, v117
	v_sub_f32_e32 v84, v80, v81
	v_pk_mul_f32 v[80:81], v[102:103], v[82:83] op_sel:[1,0] op_sel_hi:[0,1]
	v_sub_f32_e32 v85, v96, v97
	v_add_f32_e32 v86, v86, v87
	v_cvt_pk_fp8_f32 v114, v93, v94 op_sel:[0,0,1]
	v_cvt_pk_fp8_f32 v115, v89, v90 op_sel:[0,0,1]
	v_add_f32_e32 v80, v80, v81
	v_cvt_pk_fp8_f32 v104, v85, v86 op_sel:[0,0,1]
	v_cvt_pk_fp8_f32 v105, v84, v80 op_sel:[0,0,1]
	v_lshlrev_b64 v[216:217], s16, v[112:113]
	v_lshl_add_u64 v[216:217], v[168:169], 0, v[216:217]
	v_add_u32_e32 v96, s45, v174
	v_lshlrev_b32_e32 v80, 9, v96
	v_and_b32_e32 v144, 0x3ffe00, v80
	v_lshl_add_u64 v[84:85], v[156:157], 0, v[144:145]
	global_load_dwordx4 v[80:83], v[84:85], off
	s_nop 0
	global_load_dwordx4 v[84:87], v[84:85], off offset:16
	global_store_dwordx2 v[216:217], v[114:115], off
	global_store_dwordx2 v[216:217], v[104:105], off offset:128
	v_lshlrev_b32_e32 v88, 5, v174
	v_add_u32_e32 v92, s47, v88
	ds_read_b128 v[88:91], v92
	ds_read_b128 v[92:95], v92 offset:16
	v_mov_b32_e32 v98, v145
	v_mov_b32_e32 v99, v145
	v_ashrrev_i32_e32 v97, 31, v96
	s_waitcnt lgkmcnt(1)
	v_mov_b32_e32 v100, v89
	v_mov_b32_e32 v101, v90
	v_mov_b32_e32 v89, v91
	s_waitcnt lgkmcnt(0)
	v_mov_b32_e32 v90, v93
	v_mov_b32_e32 v91, v94
	v_mov_b32_e32 v93, v95
	v_pk_add_f32 v[88:89], v[100:101], v[88:89]
	v_pk_add_f32 v[90:91], v[90:91], v[92:93]
	v_add_f32_e32 v88, v88, v89
	v_add_f32_e32 v89, v90, v91
	v_fmamk_f32 v88, v88, 0x3c000000, v189
	v_fmamk_f32 v89, v89, 0x3c000000, v189
	v_rsq_f32_e32 v90, v88
	v_rsq_f32_e32 v89, v89
	v_mov_b32_e32 v88, v145
	v_mul_f32_e32 v90, v191, v90
	v_mul_f32_e32 v92, v191, v89
	v_pk_mul_f32 v[76:77], v[76:77], v[90:91] op_sel_hi:[1,0]
	v_pk_mul_f32 v[78:79], v[78:79], v[90:91] op_sel_hi:[1,0]
	v_pk_mul_f32 v[72:73], v[72:73], v[90:91] op_sel_hi:[1,0]
	v_pk_mul_f32 v[74:75], v[74:75], v[90:91] op_sel_hi:[1,0]
	v_pk_mul_f32 v[68:69], v[68:69], v[92:93] op_sel_hi:[1,0]
	v_pk_mul_f32 v[70:71], v[70:71], v[92:93] op_sel_hi:[1,0]
	v_pk_mul_f32 v[64:65], v[64:65], v[92:93] op_sel_hi:[1,0]
	v_pk_mul_f32 v[78:79], v[134:135], v[78:79]
	v_pk_mul_f32 v[76:77], v[132:133], v[76:77]
	v_pk_mul_f32 v[74:75], v[130:131], v[74:75]
	v_pk_mul_f32 v[72:73], v[128:129], v[72:73]
	v_pk_mul_f32 v[68:69], v[132:133], v[68:69]
	v_pk_mul_f32 v[66:67], v[66:67], v[92:93] op_sel_hi:[1,0]
	v_pk_mul_f32 v[70:71], v[134:135], v[70:71]
	v_pk_mul_f32 v[64:65], v[128:129], v[64:65]
	v_mov_b32_e32 v89, v145
	v_pk_mul_f32 v[66:67], v[130:131], v[66:67]
	s_waitcnt vmcnt(3)
	v_pk_mul_f32 v[90:91], v[80:81], v[76:77]
	v_pk_mul_f32 v[76:77], v[80:81], v[76:77] op_sel:[1,0] op_sel_hi:[0,1]
	v_pk_mul_f32 v[92:93], v[82:83], v[78:79]
	v_pk_mul_f32 v[78:79], v[82:83], v[78:79] op_sel:[1,0] op_sel_hi:[0,1]
	s_waitcnt vmcnt(2)
	v_pk_mul_f32 v[94:95], v[84:85], v[72:73]
	v_pk_mul_f32 v[72:73], v[84:85], v[72:73] op_sel:[1,0] op_sel_hi:[0,1]
	v_pk_mul_f32 v[100:101], v[86:87], v[74:75]
	v_pk_mul_f32 v[74:75], v[86:87], v[74:75] op_sel:[1,0] op_sel_hi:[0,1]
	v_pk_mul_f32 v[102:103], v[80:81], v[68:69]
	v_pk_mul_f32 v[68:69], v[80:81], v[68:69] op_sel:[1,0] op_sel_hi:[0,1]
	v_pk_mul_f32 v[80:81], v[82:83], v[70:71]
	v_pk_mul_f32 v[70:71], v[82:83], v[70:71] op_sel:[1,0] op_sel_hi:[0,1]
	v_pk_mul_f32 v[82:83], v[84:85], v[64:65]
	v_pk_mul_f32 v[64:65], v[84:85], v[64:65] op_sel:[1,0] op_sel_hi:[0,1]
	v_sub_f32_e32 v84, v90, v91
	v_add_f32_e32 v76, v76, v77
	v_add_f32_e32 v78, v78, v79
	v_sub_f32_e32 v79, v94, v95
	v_add_f32_e32 v72, v72, v73
	v_add_f32_e32 v74, v74, v75
	v_sub_f32_e32 v75, v102, v103
	v_add_f32_e32 v68, v68, v69
	v_cvt_pk_fp8_f32 v98, v84, v76
	v_cvt_pk_fp8_f32 v99, v79, v72
	v_cvt_pk_fp8_f32 v88, v75, v68
	v_sub_f32_e32 v68, v82, v83
	v_add_f32_e32 v64, v64, v65
	v_cvt_pk_fp8_f32 v89, v68, v64
	v_pk_mul_f32 v[64:65], v[86:87], v[66:67]
	v_sub_f32_e32 v77, v92, v93
	v_sub_f32_e32 v73, v100, v101
	v_sub_f32_e32 v68, v64, v65
	v_pk_mul_f32 v[64:65], v[86:87], v[66:67] op_sel:[1,0] op_sel_hi:[0,1]
	v_sub_f32_e32 v69, v80, v81
	v_add_f32_e32 v70, v70, v71
	v_cvt_pk_fp8_f32 v98, v77, v78 op_sel:[0,0,1]
	v_cvt_pk_fp8_f32 v99, v73, v74 op_sel:[0,0,1]
	v_add_f32_e32 v64, v64, v65
	v_cvt_pk_fp8_f32 v88, v69, v70 op_sel:[0,0,1]
	v_cvt_pk_fp8_f32 v89, v68, v64 op_sel:[0,0,1]
	v_lshlrev_b64 v[216:217], s16, v[96:97]
	v_lshl_add_u64 v[216:217], v[168:169], 0, v[216:217]
	v_add_u32_e32 v80, s45, v175
	v_lshlrev_b32_e32 v64, 9, v80
	v_and_b32_e32 v144, 0x3f9e00, v64
	v_lshl_add_u64 v[68:69], v[156:157], 0, v[144:145]
	global_load_dwordx4 v[64:67], v[68:69], off
	s_nop 0
	global_load_dwordx4 v[68:71], v[68:69], off offset:16
	global_store_dwordx2 v[216:217], v[98:99], off
	global_store_dwordx2 v[216:217], v[88:89], off offset:128
	v_lshlrev_b32_e32 v72, 5, v175
	v_add_u32_e32 v76, s47, v72
	ds_read_b128 v[72:75], v76
	ds_read_b128 v[76:79], v76 offset:16
	v_mov_b32_e32 v82, v145
	v_mov_b32_e32 v83, v145
	v_ashrrev_i32_e32 v81, 31, v80
	s_waitcnt lgkmcnt(1)
; #define LAS __attribute__((address_space(3)))
;     __device__ __forceinline__ void operator()(const f32x4 (&acc)[2][2][4][2], const Unit& u, int wr, int wc, int fr, int fq) const {
;     ...
;                 for (int m = 0; m < 4; ++m) { const int lr = ai * HALF + wr * 64 + m * 16 + fr, row = u.pm * BM + lr, spos = row & (SEQ - 1);
;                     const f32x4* rp = (const f32x4*)(rope + (size_t)spos * 128 + hc); const f32x4 r0 = rp[0], r1 = rp[1];
; #pragma unroll
;                     for (int bj = 0; bj < 2; ++bj) { const f32x4 sv = *(const LAS f32x4*)(X + (lr * 2 + bj) * 4);
;                         const float rs = __builtin_amdgcn_rsqf(((sv[0] + sv[1]) + (sv[2] + sv[3])) * (1.0f / 128.0f) + RMS_EPS) * (u.pn < 4 ? QSCALE : 1.0f);
;                         const f32x4 a = acc[ai][bj][m][0] * rs * g0, b = acc[ai][bj][m][1] * rs * g1;
;                         u32x2 w; int t0, t1;
;                         t0 = __builtin_amdgcn_cvt_pk_fp8_f32(a[0] * r0[0] - a[1] * r0[1], a[0] * r0[1] + a[1] * r0[0], 0, false);
;                         t0 = __builtin_amdgcn_cvt_pk_fp8_f32(a[2] * r0[2] - a[3] * r0[3], a[2] * r0[3] + a[3] * r0[2], t0, true);
;                         t1 = __builtin_amdgcn_cvt_pk_fp8_f32(b[0] * r1[0] - b[1] * r1[1], b[0] * r1[1] + b[1] * r1[0], 0, false);
;                         t1 = __builtin_amdgcn_cvt_pk_fp8_f32(b[2] * r1[2] - b[3] * r1[3], b[2] * r1[3] + b[3] * r1[2], t1, true);
;                         w.x = (unsigned)t0; w.y = (unsigned)t1;
;                         *(u32x2*)(base + (size_t)row * ldc + colt + bj * HALF + hc) = w; } }
	v_mov_b32_e32 v84, v73
	v_mov_b32_e32 v85, v74
	v_mov_b32_e32 v73, v75
	s_waitcnt lgkmcnt(0)
	v_mov_b32_e32 v74, v77
	v_mov_b32_e32 v75, v78
	v_mov_b32_e32 v77, v79
	v_pk_add_f32 v[72:73], v[84:85], v[72:73]
	v_pk_add_f32 v[74:75], v[74:75], v[76:77]
	v_add_f32_e32 v72, v72, v73
	v_add_f32_e32 v73, v74, v75
	v_fmamk_f32 v72, v72, 0x3c000000, v189
	v_fmamk_f32 v73, v73, 0x3c000000, v189
	v_rsq_f32_e32 v74, v72
	v_rsq_f32_e32 v73, v73
	v_mov_b32_e32 v72, v145
	v_mul_f32_e32 v74, v191, v74
	v_mul_f32_e32 v76, v191, v73
	v_pk_mul_f32 v[60:61], v[60:61], v[74:75] op_sel_hi:[1,0]
	v_pk_mul_f32 v[62:63], v[62:63], v[74:75] op_sel_hi:[1,0]
	v_pk_mul_f32 v[56:57], v[56:57], v[74:75] op_sel_hi:[1,0]
	v_pk_mul_f32 v[58:59], v[58:59], v[74:75] op_sel_hi:[1,0]
	v_pk_mul_f32 v[52:53], v[52:53], v[76:77] op_sel_hi:[1,0]
	v_pk_mul_f32 v[54:55], v[54:55], v[76:77] op_sel_hi:[1,0]
	v_pk_mul_f32 v[48:49], v[48:49], v[76:77] op_sel_hi:[1,0]
	v_pk_mul_f32 v[62:63], v[134:135], v[62:63]
	v_pk_mul_f32 v[60:61], v[132:133], v[60:61]
	v_pk_mul_f32 v[56:57], v[128:129], v[56:57]
	v_pk_mul_f32 v[50:51], v[50:51], v[76:77] op_sel_hi:[1,0]
	v_pk_mul_f32 v[58:59], v[130:131], v[58:59]
	v_pk_mul_f32 v[54:55], v[134:135], v[54:55]
	v_pk_mul_f32 v[52:53], v[132:133], v[52:53]
	v_pk_mul_f32 v[48:49], v[128:129], v[48:49]
	v_mov_b32_e32 v73, v145
	v_pk_mul_f32 v[50:51], v[130:131], v[50:51]
	s_waitcnt vmcnt(3)
	v_pk_mul_f32 v[74:75], v[64:65], v[60:61]
	v_pk_mul_f32 v[60:61], v[64:65], v[60:61] op_sel:[1,0] op_sel_hi:[0,1]
	v_pk_mul_f32 v[76:77], v[66:67], v[62:63]
	v_pk_mul_f32 v[62:63], v[66:67], v[62:63] op_sel:[1,0] op_sel_hi:[0,1]
	s_waitcnt vmcnt(2)
	v_pk_mul_f32 v[78:79], v[68:69], v[56:57]
	v_pk_mul_f32 v[56:57], v[68:69], v[56:57] op_sel:[1,0] op_sel_hi:[0,1]
	v_pk_mul_f32 v[84:85], v[70:71], v[58:59]
	v_pk_mul_f32 v[58:59], v[70:71], v[58:59] op_sel:[1,0] op_sel_hi:[0,1]
	v_pk_mul_f32 v[86:87], v[64:65], v[52:53]
	v_pk_mul_f32 v[52:53], v[64:65], v[52:53] op_sel:[1,0] op_sel_hi:[0,1]
	v_pk_mul_f32 v[64:65], v[66:67], v[54:55]
	v_pk_mul_f32 v[54:55], v[66:67], v[54:55] op_sel:[1,0] op_sel_hi:[0,1]
	v_pk_mul_f32 v[66:67], v[68:69], v[48:49]
	v_pk_mul_f32 v[48:49], v[68:69], v[48:49] op_sel:[1,0] op_sel_hi:[0,1]
	v_sub_f32_e32 v68, v74, v75
	v_add_f32_e32 v60, v60, v61
	v_add_f32_e32 v62, v62, v63
	v_sub_f32_e32 v63, v78, v79
	v_add_f32_e32 v56, v56, v57
	v_add_f32_e32 v58, v58, v59
	v_sub_f32_e32 v59, v86, v87
	v_add_f32_e32 v52, v52, v53
	v_add_f32_e32 v54, v54, v55
	v_sub_f32_e32 v55, v66, v67
	v_cvt_pk_fp8_f32 v82, v68, v60
	v_cvt_pk_fp8_f32 v83, v63, v56
	v_add_f32_e32 v48, v48, v49
	v_cvt_pk_fp8_f32 v72, v59, v52
	v_cvt_pk_fp8_f32 v73, v55, v48
	v_pk_mul_f32 v[48:49], v[70:71], v[50:51]
	v_sub_f32_e32 v61, v76, v77
	v_sub_f32_e32 v57, v84, v85
	v_sub_f32_e32 v52, v48, v49
	v_pk_mul_f32 v[48:49], v[70:71], v[50:51] op_sel:[1,0] op_sel_hi:[0,1]
	v_sub_f32_e32 v53, v64, v65
	v_cvt_pk_fp8_f32 v82, v61, v62 op_sel:[0,0,1]
	v_cvt_pk_fp8_f32 v83, v57, v58 op_sel:[0,0,1]
	v_add_f32_e32 v48, v48, v49
	v_cvt_pk_fp8_f32 v72, v53, v54 op_sel:[0,0,1]
	v_cvt_pk_fp8_f32 v73, v52, v48 op_sel:[0,0,1]
	v_lshlrev_b64 v[216:217], s16, v[80:81]
	v_lshl_add_u64 v[216:217], v[168:169], 0, v[216:217]
	v_add_u32_e32 v64, s45, v176
	v_lshlrev_b32_e32 v48, 9, v64
	v_and_b32_e32 v144, 0x3fbe00, v48
	v_lshl_add_u64 v[52:53], v[156:157], 0, v[144:145]
	global_load_dwordx4 v[48:51], v[52:53], off
	s_nop 0
	global_load_dwordx4 v[52:55], v[52:53], off offset:16
	global_store_dwordx2 v[216:217], v[82:83], off
	global_store_dwordx2 v[216:217], v[72:73], off offset:128
	v_lshlrev_b32_e32 v56, 5, v176
	v_add_u32_e32 v60, s47, v56
	ds_read_b128 v[56:59], v60
	ds_read_b128 v[60:63], v60 offset:16
	v_mov_b32_e32 v66, v145
	v_mov_b32_e32 v67, v145
	v_mov_b32_e32 v68, v145
	s_waitcnt lgkmcnt(1)
	v_mov_b32_e32 v70, v57
	v_mov_b32_e32 v71, v58
	v_mov_b32_e32 v57, v59
	s_waitcnt lgkmcnt(0)
	v_mov_b32_e32 v58, v61
	v_mov_b32_e32 v59, v62
	v_mov_b32_e32 v61, v63
	v_pk_add_f32 v[56:57], v[70:71], v[56:57]
	v_pk_add_f32 v[58:59], v[58:59], v[60:61]
	v_add_f32_e32 v56, v56, v57
	v_add_f32_e32 v57, v58, v59
	v_fmamk_f32 v56, v56, 0x3c000000, v189
	v_fmamk_f32 v57, v57, 0x3c000000, v189
	v_rsq_f32_e32 v56, v56
	v_rsq_f32_e32 v57, v57
	v_mov_b32_e32 v69, v145
	v_ashrrev_i32_e32 v65, 31, v64
	v_mul_f32_e32 v56, v191, v56
	v_mul_f32_e32 v58, v191, v57
	v_pk_mul_f32 v[44:45], v[44:45], v[56:57] op_sel_hi:[1,0]
	v_pk_mul_f32 v[46:47], v[46:47], v[56:57] op_sel_hi:[1,0]
	v_pk_mul_f32 v[40:41], v[40:41], v[56:57] op_sel_hi:[1,0]
	v_pk_mul_f32 v[42:43], v[42:43], v[56:57] op_sel_hi:[1,0]
	v_pk_mul_f32 v[36:37], v[36:37], v[58:59] op_sel_hi:[1,0]
	v_pk_mul_f32 v[38:39], v[38:39], v[58:59] op_sel_hi:[1,0]
	v_pk_mul_f32 v[32:33], v[32:33], v[58:59] op_sel_hi:[1,0]
	v_pk_mul_f32 v[46:47], v[134:135], v[46:47]
	v_pk_mul_f32 v[44:45], v[132:133], v[44:45]
	v_pk_mul_f32 v[40:41], v[128:129], v[40:41]
	v_pk_mul_f32 v[34:35], v[34:35], v[58:59] op_sel_hi:[1,0]
	v_pk_mul_f32 v[42:43], v[130:131], v[42:43]
	v_pk_mul_f32 v[38:39], v[134:135], v[38:39]
	v_pk_mul_f32 v[36:37], v[132:133], v[36:37]
	v_pk_mul_f32 v[32:33], v[128:129], v[32:33]
	v_pk_mul_f32 v[34:35], v[130:131], v[34:35]
	s_waitcnt vmcnt(3)
	v_pk_mul_f32 v[56:57], v[48:49], v[44:45]
	v_pk_mul_f32 v[44:45], v[48:49], v[44:45] op_sel:[1,0] op_sel_hi:[0,1]
	v_pk_mul_f32 v[58:59], v[50:51], v[46:47]
	v_pk_mul_f32 v[46:47], v[50:51], v[46:47] op_sel:[1,0] op_sel_hi:[0,1]
	s_waitcnt vmcnt(2)
; #define LAS __attribute__((address_space(3)))
;     __device__ __forceinline__ void operator()(const f32x4 (&acc)[2][2][4][2], const Unit& u, int wr, int wc, int fr, int fq) const {
;     ...
;                 for (int m = 0; m < 4; ++m) { const int lr = ai * HALF + wr * 64 + m * 16 + fr, row = u.pm * BM + lr, spos = row & (SEQ - 1);
;                     const f32x4* rp = (const f32x4*)(rope + (size_t)spos * 128 + hc); const f32x4 r0 = rp[0], r1 = rp[1];
; #pragma unroll
;                     for (int bj = 0; bj < 2; ++bj) { const f32x4 sv = *(const LAS f32x4*)(X + (lr * 2 + bj) * 4);
;                         const float rs = __builtin_amdgcn_rsqf(((sv[0] + sv[1]) + (sv[2] + sv[3])) * (1.0f / 128.0f) + RMS_EPS) * (u.pn < 4 ? QSCALE : 1.0f);
;                         const f32x4 a = acc[ai][bj][m][0] * rs * g0, b = acc[ai][bj][m][1] * rs * g1;
;                         u32x2 w; int t0, t1;
;                         t0 = __builtin_amdgcn_cvt_pk_fp8_f32(a[0] * r0[0] - a[1] * r0[1], a[0] * r0[1] + a[1] * r0[0], 0, false);
;                         t0 = __builtin_amdgcn_cvt_pk_fp8_f32(a[2] * r0[2] - a[3] * r0[3], a[2] * r0[3] + a[3] * r0[2], t0, true);
;                         t1 = __builtin_amdgcn_cvt_pk_fp8_f32(b[0] * r1[0] - b[1] * r1[1], b[0] * r1[1] + b[1] * r1[0], 0, false);
;                         t1 = __builtin_amdgcn_cvt_pk_fp8_f32(b[2] * r1[2] - b[3] * r1[3], b[2] * r1[3] + b[3] * r1[2], t1, true);
;                         w.x = (unsigned)t0; w.y = (unsigned)t1;
;                         *(u32x2*)(base + (size_t)row * ldc + colt + bj * HALF + hc) = w; } }
	v_pk_mul_f32 v[60:61], v[52:53], v[40:41]
	v_pk_mul_f32 v[40:41], v[52:53], v[40:41] op_sel:[1,0] op_sel_hi:[0,1]
	v_pk_mul_f32 v[62:63], v[54:55], v[42:43]
	v_pk_mul_f32 v[42:43], v[54:55], v[42:43] op_sel:[1,0] op_sel_hi:[0,1]
	v_pk_mul_f32 v[70:71], v[48:49], v[36:37]
	v_pk_mul_f32 v[36:37], v[48:49], v[36:37] op_sel:[1,0] op_sel_hi:[0,1]
	v_pk_mul_f32 v[48:49], v[50:51], v[38:39]
	v_pk_mul_f32 v[38:39], v[50:51], v[38:39] op_sel:[1,0] op_sel_hi:[0,1]
	v_pk_mul_f32 v[50:51], v[52:53], v[32:33]
	v_pk_mul_f32 v[32:33], v[52:53], v[32:33] op_sel:[1,0] op_sel_hi:[0,1]
	v_sub_f32_e32 v52, v56, v57
	v_add_f32_e32 v44, v44, v45
	v_add_f32_e32 v46, v46, v47
	v_sub_f32_e32 v47, v60, v61
	v_add_f32_e32 v40, v40, v41
	v_add_f32_e32 v42, v42, v43
	v_sub_f32_e32 v43, v70, v71
	v_add_f32_e32 v36, v36, v37
	v_add_f32_e32 v38, v38, v39
	v_sub_f32_e32 v39, v50, v51
	v_cvt_pk_fp8_f32 v66, v52, v44
	v_cvt_pk_fp8_f32 v67, v47, v40
	v_add_f32_e32 v32, v32, v33
	v_cvt_pk_fp8_f32 v68, v43, v36
	v_cvt_pk_fp8_f32 v69, v39, v32
	v_pk_mul_f32 v[32:33], v[54:55], v[34:35]
	v_sub_f32_e32 v45, v58, v59
	v_sub_f32_e32 v41, v62, v63
	v_sub_f32_e32 v36, v32, v33
	v_pk_mul_f32 v[32:33], v[54:55], v[34:35] op_sel:[1,0] op_sel_hi:[0,1]
	v_sub_f32_e32 v37, v48, v49
	v_cvt_pk_fp8_f32 v66, v45, v46 op_sel:[0,0,1]
	v_cvt_pk_fp8_f32 v67, v41, v42 op_sel:[0,0,1]
	v_add_f32_e32 v32, v32, v33
	v_cvt_pk_fp8_f32 v68, v37, v38 op_sel:[0,0,1]
	v_cvt_pk_fp8_f32 v69, v36, v32 op_sel:[0,0,1]
	v_lshlrev_b64 v[216:217], s16, v[64:65]
	v_lshl_add_u64 v[216:217], v[168:169], 0, v[216:217]
	v_add_u32_e32 v48, s45, v177
	v_lshlrev_b32_e32 v32, 9, v48
	v_and_b32_e32 v144, 0x3fde00, v32
	v_lshl_add_u64 v[36:37], v[156:157], 0, v[144:145]
	global_load_dwordx4 v[32:35], v[36:37], off
	s_nop 0
	global_load_dwordx4 v[36:39], v[36:37], off offset:16
	global_store_dwordx2 v[216:217], v[66:67], off
	global_store_dwordx2 v[216:217], v[68:69], off offset:128
	v_lshlrev_b32_e32 v40, 5, v177
	v_add_u32_e32 v44, s47, v40
	ds_read_b128 v[40:43], v44
	ds_read_b128 v[44:47], v44 offset:16
	v_mov_b32_e32 v50, v145
	v_mov_b32_e32 v51, v145
	v_mov_b32_e32 v52, v145
	s_waitcnt lgkmcnt(1)
	v_mov_b32_e32 v54, v41
	v_mov_b32_e32 v55, v42
	v_mov_b32_e32 v41, v43
	s_waitcnt lgkmcnt(0)
	v_mov_b32_e32 v42, v45
	v_mov_b32_e32 v43, v46
	v_mov_b32_e32 v45, v47
	v_pk_add_f32 v[40:41], v[54:55], v[40:41]
	v_pk_add_f32 v[42:43], v[42:43], v[44:45]
	v_add_f32_e32 v40, v40, v41
	v_add_f32_e32 v41, v42, v43
	v_fmamk_f32 v40, v40, 0x3c000000, v189
	v_fmamk_f32 v41, v41, 0x3c000000, v189
	v_rsq_f32_e32 v40, v40
	v_rsq_f32_e32 v41, v41
	v_mov_b32_e32 v53, v145
	v_ashrrev_i32_e32 v49, 31, v48
	v_mul_f32_e32 v40, v191, v40
	v_mul_f32_e32 v42, v191, v41
	v_pk_mul_f32 v[28:29], v[28:29], v[40:41] op_sel_hi:[1,0]
	v_pk_mul_f32 v[30:31], v[30:31], v[40:41] op_sel_hi:[1,0]
	v_pk_mul_f32 v[24:25], v[24:25], v[40:41] op_sel_hi:[1,0]
	v_pk_mul_f32 v[26:27], v[26:27], v[40:41] op_sel_hi:[1,0]
	v_pk_mul_f32 v[20:21], v[20:21], v[42:43] op_sel_hi:[1,0]
	v_pk_mul_f32 v[22:23], v[22:23], v[42:43] op_sel_hi:[1,0]
	v_pk_mul_f32 v[16:17], v[16:17], v[42:43] op_sel_hi:[1,0]
	v_pk_mul_f32 v[30:31], v[134:135], v[30:31]
	v_pk_mul_f32 v[28:29], v[132:133], v[28:29]
	v_pk_mul_f32 v[24:25], v[128:129], v[24:25]
	v_pk_mul_f32 v[18:19], v[18:19], v[42:43] op_sel_hi:[1,0]
	v_pk_mul_f32 v[26:27], v[130:131], v[26:27]
	v_pk_mul_f32 v[22:23], v[134:135], v[22:23]
	v_pk_mul_f32 v[20:21], v[132:133], v[20:21]
	v_pk_mul_f32 v[16:17], v[128:129], v[16:17]
	v_pk_mul_f32 v[18:19], v[130:131], v[18:19]
	s_waitcnt vmcnt(3)
	v_pk_mul_f32 v[40:41], v[32:33], v[28:29]
	v_pk_mul_f32 v[28:29], v[32:33], v[28:29] op_sel:[1,0] op_sel_hi:[0,1]
	v_pk_mul_f32 v[42:43], v[34:35], v[30:31]
	v_pk_mul_f32 v[30:31], v[34:35], v[30:31] op_sel:[1,0] op_sel_hi:[0,1]
	s_waitcnt vmcnt(2)
; #define LAS __attribute__((address_space(3)))
;     __device__ __forceinline__ void operator()(const f32x4 (&acc)[2][2][4][2], const Unit& u, int wr, int wc, int fr, int fq) const {
;     ...
;                 for (int m = 0; m < 4; ++m) { const int lr = ai * HALF + wr * 64 + m * 16 + fr, row = u.pm * BM + lr, spos = row & (SEQ - 1);
;                     const f32x4* rp = (const f32x4*)(rope + (size_t)spos * 128 + hc); const f32x4 r0 = rp[0], r1 = rp[1];
; #pragma unroll
;                     for (int bj = 0; bj < 2; ++bj) { const f32x4 sv = *(const LAS f32x4*)(X + (lr * 2 + bj) * 4);
;                         const float rs = __builtin_amdgcn_rsqf(((sv[0] + sv[1]) + (sv[2] + sv[3])) * (1.0f / 128.0f) + RMS_EPS) * (u.pn < 4 ? QSCALE : 1.0f);
;                         const f32x4 a = acc[ai][bj][m][0] * rs * g0, b = acc[ai][bj][m][1] * rs * g1;
;                         u32x2 w; int t0, t1;
;                         t0 = __builtin_amdgcn_cvt_pk_fp8_f32(a[0] * r0[0] - a[1] * r0[1], a[0] * r0[1] + a[1] * r0[0], 0, false);
;                         t0 = __builtin_amdgcn_cvt_pk_fp8_f32(a[2] * r0[2] - a[3] * r0[3], a[2] * r0[3] + a[3] * r0[2], t0, true);
;                         t1 = __builtin_amdgcn_cvt_pk_fp8_f32(b[0] * r1[0] - b[1] * r1[1], b[0] * r1[1] + b[1] * r1[0], 0, false);
;                         t1 = __builtin_amdgcn_cvt_pk_fp8_f32(b[2] * r1[2] - b[3] * r1[3], b[2] * r1[3] + b[3] * r1[2], t1, true);
;                         w.x = (unsigned)t0; w.y = (unsigned)t1;
;                         *(u32x2*)(base + (size_t)row * ldc + colt + bj * HALF + hc) = w; } }
	v_pk_mul_f32 v[44:45], v[36:37], v[24:25]
	v_pk_mul_f32 v[24:25], v[36:37], v[24:25] op_sel:[1,0] op_sel_hi:[0,1]
	v_pk_mul_f32 v[46:47], v[38:39], v[26:27]
	v_pk_mul_f32 v[26:27], v[38:39], v[26:27] op_sel:[1,0] op_sel_hi:[0,1]
	v_pk_mul_f32 v[54:55], v[32:33], v[20:21]
	v_pk_mul_f32 v[20:21], v[32:33], v[20:21] op_sel:[1,0] op_sel_hi:[0,1]
	v_pk_mul_f32 v[32:33], v[34:35], v[22:23]
	v_pk_mul_f32 v[22:23], v[34:35], v[22:23] op_sel:[1,0] op_sel_hi:[0,1]
	v_pk_mul_f32 v[34:35], v[36:37], v[16:17]
	v_pk_mul_f32 v[16:17], v[36:37], v[16:17] op_sel:[1,0] op_sel_hi:[0,1]
	v_sub_f32_e32 v36, v40, v41
	v_add_f32_e32 v28, v28, v29
	v_add_f32_e32 v30, v30, v31
	v_sub_f32_e32 v31, v44, v45
	v_add_f32_e32 v24, v24, v25
	v_add_f32_e32 v26, v26, v27
	v_sub_f32_e32 v27, v54, v55
	v_add_f32_e32 v20, v20, v21
	v_add_f32_e32 v22, v22, v23
	v_sub_f32_e32 v23, v34, v35
	v_add_f32_e32 v16, v16, v17
	v_cvt_pk_fp8_f32 v50, v36, v28
	v_cvt_pk_fp8_f32 v51, v31, v24
	v_cvt_pk_fp8_f32 v52, v27, v20
	v_cvt_pk_fp8_f32 v53, v23, v16
	v_pk_mul_f32 v[16:17], v[38:39], v[18:19]
	v_sub_f32_e32 v29, v42, v43
	v_sub_f32_e32 v25, v46, v47
	v_sub_f32_e32 v20, v16, v17
	v_pk_mul_f32 v[16:17], v[38:39], v[18:19] op_sel:[1,0] op_sel_hi:[0,1]
	v_sub_f32_e32 v21, v32, v33
	v_cvt_pk_fp8_f32 v50, v29, v30 op_sel:[0,0,1]
	v_cvt_pk_fp8_f32 v51, v25, v26 op_sel:[0,0,1]
	v_add_f32_e32 v16, v16, v17
	v_cvt_pk_fp8_f32 v52, v21, v22 op_sel:[0,0,1]
	v_cvt_pk_fp8_f32 v53, v20, v16 op_sel:[0,0,1]
	v_lshlrev_b64 v[216:217], s16, v[48:49]
	v_lshl_add_u64 v[216:217], v[168:169], 0, v[216:217]
	v_add_u32_e32 v32, s45, v178
	v_lshlrev_b32_e32 v16, 9, v32
	v_and_b32_e32 v144, 0x3ffe00, v16
	v_lshl_add_u64 v[20:21], v[156:157], 0, v[144:145]
	global_load_dwordx4 v[16:19], v[20:21], off
	s_nop 0
	global_load_dwordx4 v[20:23], v[20:21], off offset:16
	global_store_dwordx2 v[216:217], v[50:51], off
	global_store_dwordx2 v[216:217], v[52:53], off offset:128
	v_add_u32_e32 v28, s47, v179
	ds_read_b128 v[24:27], v28
	ds_read_b128 v[28:31], v28 offset:16
	v_mov_b32_e32 v34, v145
	v_mov_b32_e32 v35, v145
	v_mov_b32_e32 v36, v145
	s_waitcnt lgkmcnt(1)
	v_mov_b32_e32 v38, v25
	v_mov_b32_e32 v39, v26
	v_mov_b32_e32 v25, v27
	s_waitcnt lgkmcnt(0)
	v_mov_b32_e32 v26, v29
	v_mov_b32_e32 v27, v30
	v_mov_b32_e32 v29, v31
	v_pk_add_f32 v[24:25], v[38:39], v[24:25]
	v_pk_add_f32 v[26:27], v[26:27], v[28:29]
	v_add_f32_e32 v24, v24, v25
	v_add_f32_e32 v25, v26, v27
	v_fmamk_f32 v24, v24, 0x3c000000, v189
	v_fmamk_f32 v25, v25, 0x3c000000, v189
	v_rsq_f32_e32 v24, v24
	v_rsq_f32_e32 v25, v25
	v_mov_b32_e32 v37, v145
	v_ashrrev_i32_e32 v33, 31, v32
	v_mul_f32_e32 v24, v191, v24
	v_mul_f32_e32 v26, v191, v25
	v_pk_mul_f32 v[12:13], v[12:13], v[24:25] op_sel_hi:[1,0]
	v_pk_mul_f32 v[14:15], v[14:15], v[24:25] op_sel_hi:[1,0]
	v_pk_mul_f32 v[8:9], v[8:9], v[24:25] op_sel_hi:[1,0]
	v_pk_mul_f32 v[10:11], v[10:11], v[24:25] op_sel_hi:[1,0]
	v_pk_mul_f32 v[4:5], v[4:5], v[26:27] op_sel_hi:[1,0]
	v_pk_mul_f32 v[6:7], v[6:7], v[26:27] op_sel_hi:[1,0]
	v_pk_mul_f32 v[0:1], v[0:1], v[26:27] op_sel_hi:[1,0]
	v_pk_mul_f32 v[14:15], v[134:135], v[14:15]
	v_pk_mul_f32 v[12:13], v[132:133], v[12:13]
	v_pk_mul_f32 v[8:9], v[128:129], v[8:9]
	v_pk_mul_f32 v[2:3], v[2:3], v[26:27] op_sel_hi:[1,0]
	v_pk_mul_f32 v[10:11], v[130:131], v[10:11]
	v_pk_mul_f32 v[6:7], v[134:135], v[6:7]
	v_pk_mul_f32 v[4:5], v[132:133], v[4:5]
	v_pk_mul_f32 v[0:1], v[128:129], v[0:1]
	v_pk_mul_f32 v[2:3], v[130:131], v[2:3]
	s_waitcnt vmcnt(3)
	v_pk_mul_f32 v[24:25], v[16:17], v[12:13]
	v_pk_mul_f32 v[12:13], v[16:17], v[12:13] op_sel:[1,0] op_sel_hi:[0,1]
	v_pk_mul_f32 v[26:27], v[18:19], v[14:15]
	v_pk_mul_f32 v[14:15], v[18:19], v[14:15] op_sel:[1,0] op_sel_hi:[0,1]
	s_waitcnt vmcnt(2)
	v_pk_mul_f32 v[28:29], v[20:21], v[8:9]
	v_pk_mul_f32 v[8:9], v[20:21], v[8:9] op_sel:[1,0] op_sel_hi:[0,1]
	v_pk_mul_f32 v[30:31], v[22:23], v[10:11]
	v_pk_mul_f32 v[10:11], v[22:23], v[10:11] op_sel:[1,0] op_sel_hi:[0,1]
	v_pk_mul_f32 v[38:39], v[16:17], v[4:5]
	v_pk_mul_f32 v[4:5], v[16:17], v[4:5] op_sel:[1,0] op_sel_hi:[0,1]
	v_pk_mul_f32 v[16:17], v[18:19], v[6:7]
	v_pk_mul_f32 v[6:7], v[18:19], v[6:7] op_sel:[1,0] op_sel_hi:[0,1]
	v_pk_mul_f32 v[18:19], v[20:21], v[0:1]
	v_pk_mul_f32 v[0:1], v[20:21], v[0:1] op_sel:[1,0] op_sel_hi:[0,1]
	v_sub_f32_e32 v24, v24, v25
	v_add_f32_e32 v12, v12, v13
	v_add_f32_e32 v14, v14, v15
	v_sub_f32_e32 v15, v28, v29
	v_add_f32_e32 v8, v8, v9
	v_add_f32_e32 v10, v10, v11
	v_sub_f32_e32 v11, v38, v39
	v_add_f32_e32 v4, v4, v5
	v_add_f32_e32 v6, v6, v7
	v_sub_f32_e32 v7, v18, v19
	v_add_f32_e32 v0, v0, v1
	v_cvt_pk_fp8_f32 v34, v24, v12
	v_cvt_pk_fp8_f32 v35, v15, v8
	v_cvt_pk_fp8_f32 v36, v11, v4
	v_cvt_pk_fp8_f32 v37, v7, v0
	v_pk_mul_f32 v[20:21], v[22:23], v[2:3]
	v_sub_f32_e32 v13, v26, v27
	v_sub_f32_e32 v9, v30, v31
	v_pk_mul_f32 v[0:1], v[22:23], v[2:3] op_sel:[1,0] op_sel_hi:[0,1]
	v_sub_f32_e32 v5, v16, v17
	v_cvt_pk_fp8_f32 v34, v13, v14 op_sel:[0,0,1]
	v_cvt_pk_fp8_f32 v35, v9, v10 op_sel:[0,0,1]
	v_sub_f32_e32 v4, v20, v21
	v_add_f32_e32 v0, v0, v1
	v_cvt_pk_fp8_f32 v36, v5, v6 op_sel:[0,0,1]
	v_cvt_pk_fp8_f32 v37, v4, v0 op_sel:[0,0,1]
	v_lshlrev_b64 v[0:1], s16, v[32:33]
	v_lshl_add_u64 v[0:1], v[168:169], 0, v[0:1]
	global_store_dwordx2 v[0:1], v[34:35], off
	global_store_dwordx2 v[0:1], v[36:37], off offset:128
	s_andn2_b64 vcc, exec, s[4:5]
	s_mov_b64 s[4:5], -1
	s_cbranch_vccnz .LBB0_243
